# finalize V^T transpose: LDS chunk swizzle so 8 lanes write one full 128-B line per store (was 64 scattered 16-B pieces per store), LDS reads batched with counted waits
# speedup vs baseline: 1.0168x; 1.0168x over previous
; #define LAS __attribute__((address_space(3)))
; __device__ __forceinline__ void finalize_phase(const Params& p, LAS unsigned char* lds, int G) {
;     ...
;     LAS bf16_t* buf = (LAS bf16_t*)lds;
;     u32x4 vp[8];
;     if ((int)blockIdx.x < M / 64) {
; #pragma unroll
;         for (int i = 0; i < 8; ++i) { const int pc = tid + 512 * i, tok = pc >> 6, c = pc & 63;
;             vp[i] = *(const u32x4*)(KVRAW + (size_t)(blockIdx.x * 64 + tok) * 1024 + (c >> 3) * 128 + 64 + (c & 7) * 8); }
;     }
;     for (int t = blockIdx.x; t < M / 64; t += G) {
;         const int row0 = t * 64;
; #pragma unroll
;         for (int i = 0; i < 8; ++i) { const int pc = tid + 512 * i, tok = pc >> 6, c = pc & 63; *(LAS u32x4*)(buf + tok * 520 + c * 8) = vp[i]; }
;         __syncthreads();
;         if (t + G < M / 64) {
; #pragma unroll
;             for (int i = 0; i < 8; ++i) { const int pc = tid + 512 * i, tok = pc >> 6, c = pc & 63;
;                 vp[i] = *(const u32x4*)(KVRAW + (size_t)((t + G) * 64 + tok) * 1024 + (c >> 3) * 128 + 64 + (c & 7) * 8); }
;         }
;         const int b = row0 >> 12, s0 = row0 & 4095;
;         bf16_t* dst = VT + ((size_t)(b * 8) * 64 + tid) * SEQ + s0;
.LBB0_569:
	s_or_b64 exec, exec, s[34:35]
	v_readlane_b32 s0, v255, 12
	v_readlane_b32 s1, v255, 13
	s_and_b64 vcc, exec, s[0:1]
	s_cbranch_vccnz .LBB0_574
	v_lshlrev_b32_e32 v0, 5, v36
	v_add_u32_e32 v2, 0x200, v36
	s_waitcnt vmcnt(0)
	v_add_u32_e32 v8, 0x400, v36
	v_add_u32_e32 v10, 0x600, v36
	v_add_u32_e32 v16, 0x800, v36
	v_add_u32_e32 v18, 0xa00, v36
	v_add_u32_e32 v24, 0xc00, v36
	v_add_u32_e32 v26, 0xe00, v36
	s_lshl_b32 s4, s2, 6
	v_and_b32_e32 v34, 0x700, v0
	v_mov_b32_e32 v35, 0
	v_ashrrev_i32_e32 v45, 6, v2
	v_ashrrev_i32_e32 v44, 6, v8
	v_ashrrev_i32_e32 v43, 6, v10
	v_ashrrev_i32_e32 v42, 6, v16
	v_ashrrev_i32_e32 v46, 6, v18
	v_ashrrev_i32_e32 v47, 6, v24
	v_ashrrev_i32_e32 v39, 6, v26
	v_lshl_add_u64 v[40:41], s[12:13], 0, v[34:35]
	v_add_u32_e32 v34, s4, v118
	v_add_u32_e32 v2, s4, v45
	v_mov_b32_e32 v3, v35
	v_add_u32_e32 v8, s4, v44
	v_mov_b32_e32 v9, v35
	v_add_u32_e32 v10, s4, v43
	v_mov_b32_e32 v11, v35
	v_add_u32_e32 v16, s4, v42
	v_mov_b32_e32 v17, v35
	v_add_u32_e32 v18, s4, v46
	v_mov_b32_e32 v19, v35
	v_add_u32_e32 v24, s4, v47
	v_mov_b32_e32 v25, v35
	v_add_u32_e32 v26, s4, v39
	v_mov_b32_e32 v27, v35
	v_lshlrev_b32_e32 v32, 4, v36
	s_waitcnt lgkmcnt(0)
	v_lshlrev_b64 v[0:1], 11, v[34:35]
	v_lshlrev_b64 v[2:3], 11, v[2:3]
	v_lshlrev_b64 v[8:9], 11, v[8:9]
	v_lshlrev_b64 v[10:11], 11, v[10:11]
	v_lshlrev_b64 v[16:17], 11, v[16:17]
	v_lshlrev_b64 v[18:19], 11, v[18:19]
	v_lshlrev_b64 v[24:25], 11, v[24:25]
	v_lshlrev_b64 v[26:27], 11, v[26:27]
	v_lshl_add_u64 v[0:1], v[40:41], 0, v[0:1]
	v_and_b32_e32 v34, 0x70, v32
	v_lshl_add_u64 v[2:3], v[40:41], 0, v[2:3]
	v_lshl_add_u64 v[8:9], v[40:41], 0, v[8:9]
	v_lshl_add_u64 v[10:11], v[40:41], 0, v[10:11]
	v_lshl_add_u64 v[16:17], v[40:41], 0, v[16:17]
	v_lshl_add_u64 v[18:19], v[40:41], 0, v[18:19]
	v_lshl_add_u64 v[24:25], v[40:41], 0, v[24:25]
	v_lshl_add_u64 v[26:27], v[40:41], 0, v[26:27]
	v_lshl_add_u64 v[0:1], v[0:1], 0, v[34:35]
	v_lshl_add_u64 v[4:5], v[2:3], 0, v[34:35]
	v_lshl_add_u64 v[8:9], v[8:9], 0, v[34:35]
	v_lshl_add_u64 v[12:13], v[10:11], 0, v[34:35]
	v_lshl_add_u64 v[16:17], v[16:17], 0, v[34:35]
	v_lshl_add_u64 v[20:21], v[18:19], 0, v[34:35]
	v_lshl_add_u64 v[24:25], v[24:25], 0, v[34:35]
	v_lshl_add_u64 v[28:29], v[26:27], 0, v[34:35]
	global_load_dwordx4 v[0:3], v[0:1], off offset:128
	s_nop 0
	global_load_dwordx4 v[4:7], v[4:5], off offset:128
	s_nop 0
	global_load_dwordx4 v[8:11], v[8:9], off offset:128
	s_nop 0
	global_load_dwordx4 v[12:15], v[12:13], off offset:128
	s_nop 0
	global_load_dwordx4 v[16:19], v[16:17], off offset:128
	s_nop 0
	global_load_dwordx4 v[20:23], v[20:21], off offset:128
	s_nop 0
	global_load_dwordx4 v[24:27], v[24:25], off offset:128
	s_nop 0
	global_load_dwordx4 v[28:31], v[28:29], off offset:128
	v_and_b32_e32 v32, 0x3f0, v32
	v_ashrrev_i32_e32 v37, 31, v36
	v_add_u32_e32 v54, 0, v32
	v_lshlrev_b64 v[32:33], 13, v[36:37]
	s_movk_i32 s0, 0x410
	v_lshl_add_u64 v[32:33], s[92:93], 0, v[32:33]
	s_mov_b64 s[6:7], 0x3c000000
	v_lshl_add_u32 v38, v36, 1, 0
	v_mul_lo_u32 v36, v118, s0
	v_mul_lo_u32 v37, v45, s0
	v_mul_lo_u32 v49, v44, s0
	v_mul_lo_u32 v50, v43, s0
	v_mul_lo_u32 v51, v42, s0
	v_mul_lo_u32 v52, v46, s0
	v_mul_lo_u32 v53, v47, s0
	v_mul_lo_u32 v55, v39, s0
	s_mov_b32 s1, 0
	v_lshl_add_u64 v[32:33], v[32:33], 0, s[6:7]
	v_lshl_add_u64 v[34:35], v[40:41], 0, v[34:35]
	v_add_u32_e32 v39, s30, v39
	v_add_u32_e32 v40, s30, v47
	v_add_u32_e32 v41, s30, v46
	v_add_u32_e32 v42, s30, v42
	v_add_u32_e32 v43, s30, v43
	v_add_u32_e32 v44, s30, v44
	v_add_u32_e32 v45, s30, v45
	v_add_u32_e32 v46, s30, v118
	v_add_u32_e32 v47, v54, v36
	v_xor_b32_e32 v56, 16, v54
	v_add_u32_e32 v48, v56, v37
	v_xor_b32_e32 v56, 32, v54
	v_add_u32_e32 v49, v56, v49
	v_xor_b32_e32 v56, 48, v54
	v_add_u32_e32 v50, v56, v50
	v_xor_b32_e32 v56, 64, v54
	v_add_u32_e32 v51, v56, v51
	v_xor_b32_e32 v56, 80, v54
	v_add_u32_e32 v52, v56, v52
	v_xor_b32_e32 v56, 96, v54
	v_add_u32_e32 v53, v56, v53
	v_xor_b32_e32 v56, 112, v54
	v_add_u32_e32 v54, v56, v55
	v_lshrrev_b32_e32 v56, 6, v166
	v_bfe_u32 v57, v166, 3, 3
	v_and_b32_e32 v58, 7, v166
	v_lshl_or_b32 v60, v56, 6, v57
	v_mov_b32_e32 v61, 0
	v_lshlrev_b64 v[60:61], 13, v[60:61]
	v_lshl_add_u64 v[32:33], s[92:93], 0, v[60:61]
	v_lshl_add_u64 v[32:33], v[32:33], 0, s[6:7]
	v_lshlrev_b32_e32 v60, 4, v58
	v_mov_b32_e32 v61, 0
	v_lshl_add_u64 v[32:33], v[32:33], 0, v[60:61]
	v_mul_u32_u24_e32 v59, 0x2080, v58
	v_lshl_add_u32 v59, v56, 7, v59
	v_lshl_add_u32 v59, v57, 1, v59
	v_xor_b32_e32 v60, 0, v58
	v_lshl_add_u32 v134, v60, 4, v59
	v_xor_b32_e32 v60, 1, v58
	v_lshl_add_u32 v135, v60, 4, v59
	v_xor_b32_e32 v60, 2, v58
	v_lshl_add_u32 v136, v60, 4, v59
	v_xor_b32_e32 v60, 3, v58
	v_lshl_add_u32 v137, v60, 4, v59
	v_xor_b32_e32 v60, 4, v58
	v_lshl_add_u32 v138, v60, 4, v59
	v_xor_b32_e32 v60, 5, v58
	v_lshl_add_u32 v139, v60, 4, v59
	v_xor_b32_e32 v60, 6, v58
	v_lshl_add_u32 v140, v60, 4, v59
	v_xor_b32_e32 v60, 7, v58
	v_lshl_add_u32 v141, v60, 4, v59
	s_mov_b32 s0, s2
	s_branch .LBB0_572
; #define LAS __attribute__((address_space(3)))
; __device__ __forceinline__ void finalize_phase(const Params& p, LAS unsigned char* lds, int G) {
;     ...
;     for (int t = blockIdx.x; t < M / 64; t += G) {
;         const int row0 = t * 64;
; #pragma unroll
;         for (int i = 0; i < 8; ++i) { const int pc = tid + 512 * i, tok = pc >> 6, c = pc & 63; *(LAS u32x4*)(buf + tok * 520 + c * 8) = vp[i]; }
;         __syncthreads();
;         if (t + G < M / 64) {
; #pragma unroll
;             for (int i = 0; i < 8; ++i) { const int pc = tid + 512 * i, tok = pc >> 6, c = pc & 63;
;                 vp[i] = *(const u32x4*)(KVRAW + (size_t)((t + G) * 64 + tok) * 1024 + (c >> 3) * 128 + 64 + (c & 7) * 8); }
;         }
;         const int b = row0 >> 12, s0 = row0 & 4095;
;         bf16_t* dst = VT + ((size_t)(b * 8) * 64 + tid) * SEQ + s0;
; #pragma unroll
;         for (int i = 0; i < 8; ++i) {
;             u32x4 o;
;             o.x = (unsigned)buf[(8 * i + 0) * 520 + tid] | ((unsigned)buf[(8 * i + 1) * 520 + tid] << 16);
;             o.y = (unsigned)buf[(8 * i + 2) * 520 + tid] | ((unsigned)buf[(8 * i + 3) * 520 + tid] << 16);
;             o.z = (unsigned)buf[(8 * i + 4) * 520 + tid] | ((unsigned)buf[(8 * i + 5) * 520 + tid] << 16);
;             o.w = (unsigned)buf[(8 * i + 6) * 520 + tid] | ((unsigned)buf[(8 * i + 7) * 520 + tid] << 16);
;             *(u32x4*)(dst + 8 * i) = o;
;         }
;         __syncthreads();
;     }
.LBB0_571:
	s_ashr_i32 s0, s0, 3
	s_and_b32 s6, s0, -8
	s_ashr_i32 s7, s6, 31
	s_and_b32 s8, s4, 0xfc0
	s_lshl_b64 s[6:7], s[6:7], 19
	v_lshl_add_u64 v[36:37], v[32:33], 0, s[6:7]
	s_lshl_b32 s0, s8, 1
	v_lshl_add_u64 v[36:37], v[36:37], 0, s[0:1]
	s_add_i32 s4, s4, s30
	s_andn2_b64 vcc, exec, s[34:35]
	ds_read_u16 v64, v134 offset:0
	ds_read_u16 v68, v134 offset:1040
	ds_read_u16 v65, v134 offset:2080
	ds_read_u16 v69, v134 offset:3120
	ds_read_u16 v66, v134 offset:4160
	ds_read_u16 v70, v134 offset:5200
	ds_read_u16 v67, v134 offset:6240
	ds_read_u16 v71, v134 offset:7280
	ds_read_u16 v72, v135 offset:0
	ds_read_u16 v76, v135 offset:1040
	ds_read_u16 v73, v135 offset:2080
	ds_read_u16 v77, v135 offset:3120
	ds_read_u16 v74, v135 offset:4160
	ds_read_u16 v78, v135 offset:5200
	ds_read_u16 v75, v135 offset:6240
	ds_read_u16 v79, v135 offset:7280
	s_waitcnt lgkmcnt(8)
	v_lshl_or_b32 v64, v68, 16, v64
	v_lshl_or_b32 v65, v69, 16, v65
	v_lshl_or_b32 v66, v70, 16, v66
	v_lshl_or_b32 v67, v71, 16, v67
	global_store_dwordx4 v[36:37], v[64:67], off
	ds_read_u16 v80, v136 offset:0
	ds_read_u16 v84, v136 offset:1040
	ds_read_u16 v81, v136 offset:2080
	ds_read_u16 v85, v136 offset:3120
	ds_read_u16 v82, v136 offset:4160
	ds_read_u16 v86, v136 offset:5200
	ds_read_u16 v83, v136 offset:6240
	ds_read_u16 v87, v136 offset:7280
	s_waitcnt lgkmcnt(8)
	v_lshl_or_b32 v72, v76, 16, v72
	v_lshl_or_b32 v73, v77, 16, v73
	v_lshl_or_b32 v74, v78, 16, v74
	v_lshl_or_b32 v75, v79, 16, v75
	s_mov_b32 s0, 0x10000
	v_lshl_add_u64 v[144:145], v[36:37], 0, s[0:1]
	global_store_dwordx4 v[144:145], v[72:75], off
	ds_read_u16 v64, v137 offset:0
	ds_read_u16 v68, v137 offset:1040
	ds_read_u16 v65, v137 offset:2080
	ds_read_u16 v69, v137 offset:3120
	ds_read_u16 v66, v137 offset:4160
	ds_read_u16 v70, v137 offset:5200
	ds_read_u16 v67, v137 offset:6240
	ds_read_u16 v71, v137 offset:7280
	s_waitcnt lgkmcnt(8)
	v_lshl_or_b32 v80, v84, 16, v80
	v_lshl_or_b32 v81, v85, 16, v81
	v_lshl_or_b32 v82, v86, 16, v82
	v_lshl_or_b32 v83, v87, 16, v83
	s_mov_b32 s0, 0x20000
	v_lshl_add_u64 v[142:143], v[36:37], 0, s[0:1]
	global_store_dwordx4 v[142:143], v[80:83], off
	ds_read_u16 v72, v138 offset:0
	ds_read_u16 v76, v138 offset:1040
	ds_read_u16 v73, v138 offset:2080
	ds_read_u16 v77, v138 offset:3120
	ds_read_u16 v74, v138 offset:4160
	ds_read_u16 v78, v138 offset:5200
	ds_read_u16 v75, v138 offset:6240
	ds_read_u16 v79, v138 offset:7280
	s_waitcnt lgkmcnt(8)
	v_lshl_or_b32 v64, v68, 16, v64
	v_lshl_or_b32 v65, v69, 16, v65
	v_lshl_or_b32 v66, v70, 16, v66
	v_lshl_or_b32 v67, v71, 16, v67
	s_mov_b32 s0, 0x30000
	v_lshl_add_u64 v[144:145], v[36:37], 0, s[0:1]
	global_store_dwordx4 v[144:145], v[64:67], off
	ds_read_u16 v80, v139 offset:0
	ds_read_u16 v84, v139 offset:1040
	ds_read_u16 v81, v139 offset:2080
	ds_read_u16 v85, v139 offset:3120
	ds_read_u16 v82, v139 offset:4160
	ds_read_u16 v86, v139 offset:5200
	ds_read_u16 v83, v139 offset:6240
	ds_read_u16 v87, v139 offset:7280
	s_waitcnt lgkmcnt(8)
	v_lshl_or_b32 v72, v76, 16, v72
	v_lshl_or_b32 v73, v77, 16, v73
	v_lshl_or_b32 v74, v78, 16, v74
	v_lshl_or_b32 v75, v79, 16, v75
	s_mov_b32 s0, 0x40000
	v_lshl_add_u64 v[142:143], v[36:37], 0, s[0:1]
	global_store_dwordx4 v[142:143], v[72:75], off
	ds_read_u16 v64, v140 offset:0
	ds_read_u16 v68, v140 offset:1040
	ds_read_u16 v65, v140 offset:2080
	ds_read_u16 v69, v140 offset:3120
	ds_read_u16 v66, v140 offset:4160
	ds_read_u16 v70, v140 offset:5200
	ds_read_u16 v67, v140 offset:6240
	ds_read_u16 v71, v140 offset:7280
	s_waitcnt lgkmcnt(8)
	v_lshl_or_b32 v80, v84, 16, v80
	v_lshl_or_b32 v81, v85, 16, v81
	v_lshl_or_b32 v82, v86, 16, v82
	v_lshl_or_b32 v83, v87, 16, v83
	s_mov_b32 s0, 0x50000
	v_lshl_add_u64 v[144:145], v[36:37], 0, s[0:1]
	global_store_dwordx4 v[144:145], v[80:83], off
	ds_read_u16 v72, v141 offset:0
	ds_read_u16 v76, v141 offset:1040
	ds_read_u16 v73, v141 offset:2080
	ds_read_u16 v77, v141 offset:3120
	ds_read_u16 v74, v141 offset:4160
	ds_read_u16 v78, v141 offset:5200
	ds_read_u16 v75, v141 offset:6240
	ds_read_u16 v79, v141 offset:7280
	s_waitcnt lgkmcnt(8)
	v_lshl_or_b32 v64, v68, 16, v64
	v_lshl_or_b32 v65, v69, 16, v65
	v_lshl_or_b32 v66, v70, 16, v66
	v_lshl_or_b32 v67, v71, 16, v67
	s_mov_b32 s0, 0x60000
	v_lshl_add_u64 v[142:143], v[36:37], 0, s[0:1]
	global_store_dwordx4 v[142:143], v[64:67], off
	s_waitcnt lgkmcnt(0)
	v_lshl_or_b32 v72, v76, 16, v72
	v_lshl_or_b32 v73, v77, 16, v73
	v_lshl_or_b32 v74, v78, 16, v74
	v_lshl_or_b32 v75, v79, 16, v75
	s_mov_b32 s0, 0x70000
	v_lshl_add_u64 v[144:145], v[36:37], 0, s[0:1]
	global_store_dwordx4 v[144:145], v[72:75], off
	s_mov_b32 s0, s5
	s_barrier
	s_cbranch_vccz .LBB0_574
